# P10 SwiGLU epilogue hand-rewritten: shifts/rowss loaded once per tile, scalar fma chain instead of pk ops+shuffles, stores not waited
# speedup vs baseline: 1.0235x; 1.0116x over previous
.LBB0_1125:
	s_lshl_b32 s12, s28, 8
	s_add_i32 s12, s12, s51
	v_or_b32_e32 v148, s12, v139
	v_ashrrev_i32_e32 v149, 31, v148
	v_lshl_add_u64 v[172:173], v[148:149], 2, s[8:9]
	global_load_dword v230, v[172:173], off
	global_load_dword v231, v[172:173], off offset:64
	global_load_dword v232, v[172:173], off offset:128
	global_load_dword v233, v[172:173], off offset:192
	global_load_dword v234, v[172:173], off offset:512
	global_load_dword v235, v[172:173], off offset:576
	global_load_dword v236, v[172:173], off offset:640
	global_load_dword v237, v[172:173], off offset:704
	s_ashr_i32 s13, s12, 13
	s_mul_i32 s40, s13, 0x1600
	s_lshl_b32 s36, s29, 8
	s_lshl_b32 s28, s29, 7
	s_ashr_i32 s41, s40, 31
	s_ashr_i32 s37, s36, 31
	s_ashr_i32 s29, s28, 31
	s_lshl_b64 s[40:41], s[40:41], 2
	s_add_u32 s13, s52, s40
	s_addc_u32 s21, s53, s41
	s_lshl_b64 s[36:37], s[36:37], 2
	s_add_u32 s40, s13, s36
	s_addc_u32 s41, s21, s37
	v_lshlrev_b32_e32 v149, 2, v138
	global_load_dwordx4 v[160:163], v149, s[40:41]
	global_load_dwordx4 v[156:159], v149, s[40:41] offset:512
	global_load_dwordx4 v[168:171], v149, s[40:41] offset:16
	global_load_dwordx4 v[164:167], v149, s[40:41] offset:528
	s_lshl_b64 s[28:29], s[28:29], 1
	s_mov_b32 s98, 0x16000
	s_mov_b32 s99, 0
	s_mov_b32 s100, 0x6e000
	s_mov_b32 s101, 0
	v_mov_b64_e32 v[174:175], s[92:93]
	v_lshlrev_b32_e32 v136, 1, v138
	v_mad_i64_i32 v[246:247], s[44:45], v148, s59, v[174:175]
	v_lshl_add_u64 v[246:247], v[246:247], 0, s[28:29]
	v_lshl_add_u64 v[246:247], v[246:247], 0, v[136:137]
	s_waitcnt vmcnt(0)
	v_fmamk_f32 v230, v230, 0x3a800000, v154
	v_fmamk_f32 v231, v231, 0x3a800000, v154
	v_fmamk_f32 v232, v232, 0x3a800000, v154
	v_fmamk_f32 v233, v233, 0x3a800000, v154
	v_fmamk_f32 v234, v234, 0x3a800000, v154
	v_fmamk_f32 v235, v235, 0x3a800000, v154
	v_fmamk_f32 v236, v236, 0x3a800000, v154
	v_fmamk_f32 v237, v237, 0x3a800000, v154
	v_rsq_f32_e32 v230, v230
	v_rsq_f32_e32 v231, v231
	v_rsq_f32_e32 v232, v232
	v_rsq_f32_e32 v233, v233
	v_rsq_f32_e32 v234, v234
	v_rsq_f32_e32 v235, v235
	v_rsq_f32_e32 v236, v236
	v_rsq_f32_e32 v237, v237
	v_fma_f32 v124, v124, v230, v160
	v_fma_f32 v125, v125, v230, v161
	v_fma_f32 v126, v126, v230, v162
	v_fma_f32 v127, v127, v230, v163
	v_fma_f32 v120, v120, v230, v168
	v_fma_f32 v121, v121, v230, v169
	v_fma_f32 v122, v122, v230, v170
	v_fma_f32 v123, v123, v230, v171
	v_mul_f32_e32 v238, 0xbfb8aa3b, v124
	v_mul_f32_e32 v239, 0xbfb8aa3b, v125
	v_mul_f32_e32 v240, 0xbfb8aa3b, v126
	v_mul_f32_e32 v241, 0xbfb8aa3b, v127
	v_mul_f32_e32 v242, 0xbfb8aa3b, v120
	v_mul_f32_e32 v243, 0xbfb8aa3b, v121
	v_mul_f32_e32 v244, 0xbfb8aa3b, v122
	v_mul_f32_e32 v245, 0xbfb8aa3b, v123
	v_exp_f32_e32 v238, v238
	v_exp_f32_e32 v239, v239
	v_exp_f32_e32 v240, v240
	v_exp_f32_e32 v241, v241
	v_exp_f32_e32 v242, v242
	v_exp_f32_e32 v243, v243
	v_exp_f32_e32 v244, v244
	v_exp_f32_e32 v245, v245
	v_fma_f32 v116, v116, v230, v156
	v_fma_f32 v117, v117, v230, v157
	v_fma_f32 v118, v118, v230, v158
	v_fma_f32 v119, v119, v230, v159
	v_fma_f32 v112, v112, v230, v164
	v_fma_f32 v113, v113, v230, v165
	v_fma_f32 v114, v114, v230, v166
	v_fma_f32 v115, v115, v230, v167
	v_add_f32_e32 v238, 1.0, v238
	v_add_f32_e32 v239, 1.0, v239
	v_add_f32_e32 v240, 1.0, v240
	v_add_f32_e32 v241, 1.0, v241
	v_add_f32_e32 v242, 1.0, v242
	v_add_f32_e32 v243, 1.0, v243
	v_add_f32_e32 v244, 1.0, v244
	v_add_f32_e32 v245, 1.0, v245
	v_rcp_f32_e32 v238, v238
	v_rcp_f32_e32 v239, v239
	v_rcp_f32_e32 v240, v240
	v_rcp_f32_e32 v241, v241
	v_rcp_f32_e32 v242, v242
	v_rcp_f32_e32 v243, v243
	v_rcp_f32_e32 v244, v244
	v_rcp_f32_e32 v245, v245
	v_mul_f32_e32 v124, v124, v116
	v_mul_f32_e32 v125, v125, v117
	v_mul_f32_e32 v126, v126, v118
	v_mul_f32_e32 v127, v127, v119
	v_mul_f32_e32 v120, v120, v112
	v_mul_f32_e32 v121, v121, v113
	v_mul_f32_e32 v122, v122, v114
	v_mul_f32_e32 v123, v123, v115
	v_mul_f32_e32 v124, v124, v238
	v_mul_f32_e32 v125, v125, v239
	v_mul_f32_e32 v126, v126, v240
	v_mul_f32_e32 v127, v127, v241
	v_mul_f32_e32 v120, v120, v242
	v_mul_f32_e32 v121, v121, v243
	v_mul_f32_e32 v122, v122, v244
	v_mul_f32_e32 v123, v123, v245
	v_cvt_pk_bf16_f32 v112, v124, v125
	v_cvt_pk_bf16_f32 v113, v126, v127
	v_cvt_pk_bf16_f32 v114, v120, v121
	v_cvt_pk_bf16_f32 v115, v122, v123
	global_store_dwordx4 v[246:247], v[112:115], off
	v_lshl_add_u64 v[246:247], v[246:247], 0, s[98:99]
	v_fma_f32 v108, v108, v231, v160
	v_fma_f32 v109, v109, v231, v161
	v_fma_f32 v110, v110, v231, v162
	v_fma_f32 v111, v111, v231, v163
	v_fma_f32 v104, v104, v231, v168
	v_fma_f32 v105, v105, v231, v169
	v_fma_f32 v106, v106, v231, v170
	v_fma_f32 v107, v107, v231, v171
	v_mul_f32_e32 v238, 0xbfb8aa3b, v108
	v_mul_f32_e32 v239, 0xbfb8aa3b, v109
	v_mul_f32_e32 v240, 0xbfb8aa3b, v110
	v_mul_f32_e32 v241, 0xbfb8aa3b, v111
	v_mul_f32_e32 v242, 0xbfb8aa3b, v104
	v_mul_f32_e32 v243, 0xbfb8aa3b, v105
	v_mul_f32_e32 v244, 0xbfb8aa3b, v106
	v_mul_f32_e32 v245, 0xbfb8aa3b, v107
	v_exp_f32_e32 v238, v238
	v_exp_f32_e32 v239, v239
	v_exp_f32_e32 v240, v240
	v_exp_f32_e32 v241, v241
	v_exp_f32_e32 v242, v242
	v_exp_f32_e32 v243, v243
	v_exp_f32_e32 v244, v244
	v_exp_f32_e32 v245, v245
	v_fma_f32 v100, v100, v231, v156
	v_fma_f32 v101, v101, v231, v157
	v_fma_f32 v102, v102, v231, v158
	v_fma_f32 v103, v103, v231, v159
	v_fma_f32 v96, v96, v231, v164
	v_fma_f32 v97, v97, v231, v165
	v_fma_f32 v98, v98, v231, v166
	v_fma_f32 v99, v99, v231, v167
	v_add_f32_e32 v238, 1.0, v238
	v_add_f32_e32 v239, 1.0, v239
	v_add_f32_e32 v240, 1.0, v240
	v_add_f32_e32 v241, 1.0, v241
	v_add_f32_e32 v242, 1.0, v242
	v_add_f32_e32 v243, 1.0, v243
	v_add_f32_e32 v244, 1.0, v244
	v_add_f32_e32 v245, 1.0, v245
	v_rcp_f32_e32 v238, v238
	v_rcp_f32_e32 v239, v239
	v_rcp_f32_e32 v240, v240
	v_rcp_f32_e32 v241, v241
	v_rcp_f32_e32 v242, v242
	v_rcp_f32_e32 v243, v243
	v_rcp_f32_e32 v244, v244
	v_rcp_f32_e32 v245, v245
	v_mul_f32_e32 v108, v108, v100
	v_mul_f32_e32 v109, v109, v101
	v_mul_f32_e32 v110, v110, v102
	v_mul_f32_e32 v111, v111, v103
	v_mul_f32_e32 v104, v104, v96
	v_mul_f32_e32 v105, v105, v97
	v_mul_f32_e32 v106, v106, v98
	v_mul_f32_e32 v107, v107, v99
	v_mul_f32_e32 v108, v108, v238
	v_mul_f32_e32 v109, v109, v239
	v_mul_f32_e32 v110, v110, v240
	v_mul_f32_e32 v111, v111, v241
	v_mul_f32_e32 v104, v104, v242
	v_mul_f32_e32 v105, v105, v243
	v_mul_f32_e32 v106, v106, v244
	v_mul_f32_e32 v107, v107, v245
	v_cvt_pk_bf16_f32 v96, v108, v109
	v_cvt_pk_bf16_f32 v97, v110, v111
	v_cvt_pk_bf16_f32 v98, v104, v105
	v_cvt_pk_bf16_f32 v99, v106, v107
	global_store_dwordx4 v[246:247], v[96:99], off
	v_lshl_add_u64 v[246:247], v[246:247], 0, s[98:99]
	v_fma_f32 v92, v92, v232, v160
	v_fma_f32 v93, v93, v232, v161
	v_fma_f32 v94, v94, v232, v162
	v_fma_f32 v95, v95, v232, v163
	v_fma_f32 v88, v88, v232, v168
	v_fma_f32 v89, v89, v232, v169
	v_fma_f32 v90, v90, v232, v170
	v_fma_f32 v91, v91, v232, v171
	v_mul_f32_e32 v238, 0xbfb8aa3b, v92
	v_mul_f32_e32 v239, 0xbfb8aa3b, v93
	v_mul_f32_e32 v240, 0xbfb8aa3b, v94
	v_mul_f32_e32 v241, 0xbfb8aa3b, v95
	v_mul_f32_e32 v242, 0xbfb8aa3b, v88
	v_mul_f32_e32 v243, 0xbfb8aa3b, v89
	v_mul_f32_e32 v244, 0xbfb8aa3b, v90
	v_mul_f32_e32 v245, 0xbfb8aa3b, v91
	v_exp_f32_e32 v238, v238
	v_exp_f32_e32 v239, v239
	v_exp_f32_e32 v240, v240
	v_exp_f32_e32 v241, v241
	v_exp_f32_e32 v242, v242
	v_exp_f32_e32 v243, v243
	v_exp_f32_e32 v244, v244
	v_exp_f32_e32 v245, v245
	v_fma_f32 v84, v84, v232, v156
	v_fma_f32 v85, v85, v232, v157
	v_fma_f32 v86, v86, v232, v158
	v_fma_f32 v87, v87, v232, v159
	v_fma_f32 v80, v80, v232, v164
	v_fma_f32 v81, v81, v232, v165
	v_fma_f32 v82, v82, v232, v166
	v_fma_f32 v83, v83, v232, v167
	v_add_f32_e32 v238, 1.0, v238
	v_add_f32_e32 v239, 1.0, v239
	v_add_f32_e32 v240, 1.0, v240
	v_add_f32_e32 v241, 1.0, v241
	v_add_f32_e32 v242, 1.0, v242
	v_add_f32_e32 v243, 1.0, v243
	v_add_f32_e32 v244, 1.0, v244
	v_add_f32_e32 v245, 1.0, v245
	v_rcp_f32_e32 v238, v238
	v_rcp_f32_e32 v239, v239
	v_rcp_f32_e32 v240, v240
	v_rcp_f32_e32 v241, v241
	v_rcp_f32_e32 v242, v242
	v_rcp_f32_e32 v243, v243
	v_rcp_f32_e32 v244, v244
	v_rcp_f32_e32 v245, v245
	v_mul_f32_e32 v92, v92, v84
	v_mul_f32_e32 v93, v93, v85
	v_mul_f32_e32 v94, v94, v86
	v_mul_f32_e32 v95, v95, v87
	v_mul_f32_e32 v88, v88, v80
	v_mul_f32_e32 v89, v89, v81
	v_mul_f32_e32 v90, v90, v82
	v_mul_f32_e32 v91, v91, v83
	v_mul_f32_e32 v92, v92, v238
	v_mul_f32_e32 v93, v93, v239
	v_mul_f32_e32 v94, v94, v240
	v_mul_f32_e32 v95, v95, v241
	v_mul_f32_e32 v88, v88, v242
	v_mul_f32_e32 v89, v89, v243
	v_mul_f32_e32 v90, v90, v244
	v_mul_f32_e32 v91, v91, v245
	v_cvt_pk_bf16_f32 v80, v92, v93
	v_cvt_pk_bf16_f32 v81, v94, v95
	v_cvt_pk_bf16_f32 v82, v88, v89
	v_cvt_pk_bf16_f32 v83, v90, v91
	global_store_dwordx4 v[246:247], v[80:83], off
	v_lshl_add_u64 v[246:247], v[246:247], 0, s[98:99]
	v_fma_f32 v76, v76, v233, v160
	v_fma_f32 v77, v77, v233, v161
	v_fma_f32 v78, v78, v233, v162
	v_fma_f32 v79, v79, v233, v163
	v_fma_f32 v72, v72, v233, v168
	v_fma_f32 v73, v73, v233, v169
	v_fma_f32 v74, v74, v233, v170
	v_fma_f32 v75, v75, v233, v171
	v_mul_f32_e32 v238, 0xbfb8aa3b, v76
	v_mul_f32_e32 v239, 0xbfb8aa3b, v77
	v_mul_f32_e32 v240, 0xbfb8aa3b, v78
	v_mul_f32_e32 v241, 0xbfb8aa3b, v79
	v_mul_f32_e32 v242, 0xbfb8aa3b, v72
	v_mul_f32_e32 v243, 0xbfb8aa3b, v73
	v_mul_f32_e32 v244, 0xbfb8aa3b, v74
	v_mul_f32_e32 v245, 0xbfb8aa3b, v75
	v_exp_f32_e32 v238, v238
	v_exp_f32_e32 v239, v239
	v_exp_f32_e32 v240, v240
	v_exp_f32_e32 v241, v241
	v_exp_f32_e32 v242, v242
	v_exp_f32_e32 v243, v243
	v_exp_f32_e32 v244, v244
	v_exp_f32_e32 v245, v245
	v_fma_f32 v68, v68, v233, v156
	v_fma_f32 v69, v69, v233, v157
	v_fma_f32 v70, v70, v233, v158
	v_fma_f32 v71, v71, v233, v159
	v_fma_f32 v64, v64, v233, v164
	v_fma_f32 v65, v65, v233, v165
	v_fma_f32 v66, v66, v233, v166
	v_fma_f32 v67, v67, v233, v167
	v_add_f32_e32 v238, 1.0, v238
	v_add_f32_e32 v239, 1.0, v239
	v_add_f32_e32 v240, 1.0, v240
	v_add_f32_e32 v241, 1.0, v241
	v_add_f32_e32 v242, 1.0, v242
	v_add_f32_e32 v243, 1.0, v243
	v_add_f32_e32 v244, 1.0, v244
	v_add_f32_e32 v245, 1.0, v245
	v_rcp_f32_e32 v238, v238
	v_rcp_f32_e32 v239, v239
	v_rcp_f32_e32 v240, v240
	v_rcp_f32_e32 v241, v241
	v_rcp_f32_e32 v242, v242
	v_rcp_f32_e32 v243, v243
	v_rcp_f32_e32 v244, v244
	v_rcp_f32_e32 v245, v245
	v_mul_f32_e32 v76, v76, v68
	v_mul_f32_e32 v77, v77, v69
	v_mul_f32_e32 v78, v78, v70
	v_mul_f32_e32 v79, v79, v71
	v_mul_f32_e32 v72, v72, v64
	v_mul_f32_e32 v73, v73, v65
	v_mul_f32_e32 v74, v74, v66
	v_mul_f32_e32 v75, v75, v67
	v_mul_f32_e32 v76, v76, v238
	v_mul_f32_e32 v77, v77, v239
	v_mul_f32_e32 v78, v78, v240
	v_mul_f32_e32 v79, v79, v241
	v_mul_f32_e32 v72, v72, v242
	v_mul_f32_e32 v73, v73, v243
	v_mul_f32_e32 v74, v74, v244
	v_mul_f32_e32 v75, v75, v245
	v_cvt_pk_bf16_f32 v64, v76, v77
	v_cvt_pk_bf16_f32 v65, v78, v79
	v_cvt_pk_bf16_f32 v66, v72, v73
	v_cvt_pk_bf16_f32 v67, v74, v75
	global_store_dwordx4 v[246:247], v[64:67], off
	v_lshl_add_u64 v[246:247], v[246:247], 0, s[100:101]
	v_fma_f32 v60, v60, v234, v160
	v_fma_f32 v61, v61, v234, v161
	v_fma_f32 v62, v62, v234, v162
	v_fma_f32 v63, v63, v234, v163
	v_fma_f32 v56, v56, v234, v168
	v_fma_f32 v57, v57, v234, v169
	v_fma_f32 v58, v58, v234, v170
	v_fma_f32 v59, v59, v234, v171
	v_mul_f32_e32 v238, 0xbfb8aa3b, v60
	v_mul_f32_e32 v239, 0xbfb8aa3b, v61
	v_mul_f32_e32 v240, 0xbfb8aa3b, v62
	v_mul_f32_e32 v241, 0xbfb8aa3b, v63
	v_mul_f32_e32 v242, 0xbfb8aa3b, v56
	v_mul_f32_e32 v243, 0xbfb8aa3b, v57
	v_mul_f32_e32 v244, 0xbfb8aa3b, v58
	v_mul_f32_e32 v245, 0xbfb8aa3b, v59
	v_exp_f32_e32 v238, v238
	v_exp_f32_e32 v239, v239
	v_exp_f32_e32 v240, v240
	v_exp_f32_e32 v241, v241
	v_exp_f32_e32 v242, v242
	v_exp_f32_e32 v243, v243
	v_exp_f32_e32 v244, v244
	v_exp_f32_e32 v245, v245
	v_fma_f32 v52, v52, v234, v156
	v_fma_f32 v53, v53, v234, v157
	v_fma_f32 v54, v54, v234, v158
	v_fma_f32 v55, v55, v234, v159
	v_fma_f32 v48, v48, v234, v164
	v_fma_f32 v49, v49, v234, v165
	v_fma_f32 v50, v50, v234, v166
	v_fma_f32 v51, v51, v234, v167
	v_add_f32_e32 v238, 1.0, v238
	v_add_f32_e32 v239, 1.0, v239
	v_add_f32_e32 v240, 1.0, v240
	v_add_f32_e32 v241, 1.0, v241
	v_add_f32_e32 v242, 1.0, v242
	v_add_f32_e32 v243, 1.0, v243
	v_add_f32_e32 v244, 1.0, v244
	v_add_f32_e32 v245, 1.0, v245
	v_rcp_f32_e32 v238, v238
	v_rcp_f32_e32 v239, v239
	v_rcp_f32_e32 v240, v240
	v_rcp_f32_e32 v241, v241
	v_rcp_f32_e32 v242, v242
	v_rcp_f32_e32 v243, v243
	v_rcp_f32_e32 v244, v244
	v_rcp_f32_e32 v245, v245
	v_mul_f32_e32 v60, v60, v52
	v_mul_f32_e32 v61, v61, v53
	v_mul_f32_e32 v62, v62, v54
	v_mul_f32_e32 v63, v63, v55
	v_mul_f32_e32 v56, v56, v48
	v_mul_f32_e32 v57, v57, v49
	v_mul_f32_e32 v58, v58, v50
	v_mul_f32_e32 v59, v59, v51
	v_mul_f32_e32 v60, v60, v238
	v_mul_f32_e32 v61, v61, v239
	v_mul_f32_e32 v62, v62, v240
	v_mul_f32_e32 v63, v63, v241
	v_mul_f32_e32 v56, v56, v242
	v_mul_f32_e32 v57, v57, v243
	v_mul_f32_e32 v58, v58, v244
	v_mul_f32_e32 v59, v59, v245
	v_cvt_pk_bf16_f32 v48, v60, v61
	v_cvt_pk_bf16_f32 v49, v62, v63
	v_cvt_pk_bf16_f32 v50, v56, v57
	v_cvt_pk_bf16_f32 v51, v58, v59
	global_store_dwordx4 v[246:247], v[48:51], off
	v_lshl_add_u64 v[246:247], v[246:247], 0, s[98:99]
	v_fma_f32 v44, v44, v235, v160
	v_fma_f32 v45, v45, v235, v161
	v_fma_f32 v46, v46, v235, v162
	v_fma_f32 v47, v47, v235, v163
	v_fma_f32 v40, v40, v235, v168
	v_fma_f32 v41, v41, v235, v169
	v_fma_f32 v42, v42, v235, v170
	v_fma_f32 v43, v43, v235, v171
	v_mul_f32_e32 v238, 0xbfb8aa3b, v44
	v_mul_f32_e32 v239, 0xbfb8aa3b, v45
	v_mul_f32_e32 v240, 0xbfb8aa3b, v46
	v_mul_f32_e32 v241, 0xbfb8aa3b, v47
	v_mul_f32_e32 v242, 0xbfb8aa3b, v40
	v_mul_f32_e32 v243, 0xbfb8aa3b, v41
	v_mul_f32_e32 v244, 0xbfb8aa3b, v42
	v_mul_f32_e32 v245, 0xbfb8aa3b, v43
	v_exp_f32_e32 v238, v238
	v_exp_f32_e32 v239, v239
	v_exp_f32_e32 v240, v240
	v_exp_f32_e32 v241, v241
	v_exp_f32_e32 v242, v242
	v_exp_f32_e32 v243, v243
	v_exp_f32_e32 v244, v244
	v_exp_f32_e32 v245, v245
	v_fma_f32 v36, v36, v235, v156
	v_fma_f32 v37, v37, v235, v157
	v_fma_f32 v38, v38, v235, v158
	v_fma_f32 v39, v39, v235, v159
	v_fma_f32 v32, v32, v235, v164
	v_fma_f32 v33, v33, v235, v165
	v_fma_f32 v34, v34, v235, v166
	v_fma_f32 v35, v35, v235, v167
	v_add_f32_e32 v238, 1.0, v238
	v_add_f32_e32 v239, 1.0, v239
	v_add_f32_e32 v240, 1.0, v240
	v_add_f32_e32 v241, 1.0, v241
	v_add_f32_e32 v242, 1.0, v242
	v_add_f32_e32 v243, 1.0, v243
	v_add_f32_e32 v244, 1.0, v244
	v_add_f32_e32 v245, 1.0, v245
	v_rcp_f32_e32 v238, v238
	v_rcp_f32_e32 v239, v239
	v_rcp_f32_e32 v240, v240
	v_rcp_f32_e32 v241, v241
	v_rcp_f32_e32 v242, v242
	v_rcp_f32_e32 v243, v243
	v_rcp_f32_e32 v244, v244
	v_rcp_f32_e32 v245, v245
	v_mul_f32_e32 v44, v44, v36
	v_mul_f32_e32 v45, v45, v37
	v_mul_f32_e32 v46, v46, v38
	v_mul_f32_e32 v47, v47, v39
	v_mul_f32_e32 v40, v40, v32
	v_mul_f32_e32 v41, v41, v33
	v_mul_f32_e32 v42, v42, v34
	v_mul_f32_e32 v43, v43, v35
	v_mul_f32_e32 v44, v44, v238
	v_mul_f32_e32 v45, v45, v239
	v_mul_f32_e32 v46, v46, v240
	v_mul_f32_e32 v47, v47, v241
	v_mul_f32_e32 v40, v40, v242
	v_mul_f32_e32 v41, v41, v243
	v_mul_f32_e32 v42, v42, v244
	v_mul_f32_e32 v43, v43, v245
	v_cvt_pk_bf16_f32 v32, v44, v45
	v_cvt_pk_bf16_f32 v33, v46, v47
	v_cvt_pk_bf16_f32 v34, v40, v41
	v_cvt_pk_bf16_f32 v35, v42, v43
	global_store_dwordx4 v[246:247], v[32:35], off
	v_lshl_add_u64 v[246:247], v[246:247], 0, s[98:99]
	v_fma_f32 v28, v28, v236, v160
	v_fma_f32 v29, v29, v236, v161
	v_fma_f32 v30, v30, v236, v162
	v_fma_f32 v31, v31, v236, v163
	v_fma_f32 v24, v24, v236, v168
	v_fma_f32 v25, v25, v236, v169
	v_fma_f32 v26, v26, v236, v170
	v_fma_f32 v27, v27, v236, v171
	v_mul_f32_e32 v238, 0xbfb8aa3b, v28
	v_mul_f32_e32 v239, 0xbfb8aa3b, v29
	v_mul_f32_e32 v240, 0xbfb8aa3b, v30
	v_mul_f32_e32 v241, 0xbfb8aa3b, v31
	v_mul_f32_e32 v242, 0xbfb8aa3b, v24
	v_mul_f32_e32 v243, 0xbfb8aa3b, v25
	v_mul_f32_e32 v244, 0xbfb8aa3b, v26
	v_mul_f32_e32 v245, 0xbfb8aa3b, v27
	v_exp_f32_e32 v238, v238
	v_exp_f32_e32 v239, v239
	v_exp_f32_e32 v240, v240
	v_exp_f32_e32 v241, v241
	v_exp_f32_e32 v242, v242
	v_exp_f32_e32 v243, v243
	v_exp_f32_e32 v244, v244
	v_exp_f32_e32 v245, v245
	v_fma_f32 v20, v20, v236, v156
	v_fma_f32 v21, v21, v236, v157
	v_fma_f32 v22, v22, v236, v158
	v_fma_f32 v23, v23, v236, v159
	v_fma_f32 v16, v16, v236, v164
	v_fma_f32 v17, v17, v236, v165
	v_fma_f32 v18, v18, v236, v166
	v_fma_f32 v19, v19, v236, v167
	v_add_f32_e32 v238, 1.0, v238
	v_add_f32_e32 v239, 1.0, v239
	v_add_f32_e32 v240, 1.0, v240
	v_add_f32_e32 v241, 1.0, v241
	v_add_f32_e32 v242, 1.0, v242
	v_add_f32_e32 v243, 1.0, v243
	v_add_f32_e32 v244, 1.0, v244
	v_add_f32_e32 v245, 1.0, v245
	v_rcp_f32_e32 v238, v238
	v_rcp_f32_e32 v239, v239
	v_rcp_f32_e32 v240, v240
	v_rcp_f32_e32 v241, v241
	v_rcp_f32_e32 v242, v242
	v_rcp_f32_e32 v243, v243
	v_rcp_f32_e32 v244, v244
	v_rcp_f32_e32 v245, v245
	v_mul_f32_e32 v28, v28, v20
	v_mul_f32_e32 v29, v29, v21
	v_mul_f32_e32 v30, v30, v22
	v_mul_f32_e32 v31, v31, v23
	v_mul_f32_e32 v24, v24, v16
	v_mul_f32_e32 v25, v25, v17
	v_mul_f32_e32 v26, v26, v18
	v_mul_f32_e32 v27, v27, v19
	v_mul_f32_e32 v28, v28, v238
	v_mul_f32_e32 v29, v29, v239
	v_mul_f32_e32 v30, v30, v240
	v_mul_f32_e32 v31, v31, v241
	v_mul_f32_e32 v24, v24, v242
	v_mul_f32_e32 v25, v25, v243
	v_mul_f32_e32 v26, v26, v244
	v_mul_f32_e32 v27, v27, v245
	v_cvt_pk_bf16_f32 v16, v28, v29
	v_cvt_pk_bf16_f32 v17, v30, v31
	v_cvt_pk_bf16_f32 v18, v24, v25
	v_cvt_pk_bf16_f32 v19, v26, v27
	global_store_dwordx4 v[246:247], v[16:19], off
	v_lshl_add_u64 v[246:247], v[246:247], 0, s[98:99]
	v_fma_f32 v12, v12, v237, v160
	v_fma_f32 v13, v13, v237, v161
	v_fma_f32 v14, v14, v237, v162
	v_fma_f32 v15, v15, v237, v163
	v_fma_f32 v8, v8, v237, v168
	v_fma_f32 v9, v9, v237, v169
	v_fma_f32 v10, v10, v237, v170
	v_fma_f32 v11, v11, v237, v171
	v_mul_f32_e32 v238, 0xbfb8aa3b, v12
	v_mul_f32_e32 v239, 0xbfb8aa3b, v13
	v_mul_f32_e32 v240, 0xbfb8aa3b, v14
	v_mul_f32_e32 v241, 0xbfb8aa3b, v15
	v_mul_f32_e32 v242, 0xbfb8aa3b, v8
	v_mul_f32_e32 v243, 0xbfb8aa3b, v9
	v_mul_f32_e32 v244, 0xbfb8aa3b, v10
	v_mul_f32_e32 v245, 0xbfb8aa3b, v11
	v_exp_f32_e32 v238, v238
	v_exp_f32_e32 v239, v239
	v_exp_f32_e32 v240, v240
	v_exp_f32_e32 v241, v241
	v_exp_f32_e32 v242, v242
	v_exp_f32_e32 v243, v243
	v_exp_f32_e32 v244, v244
	v_exp_f32_e32 v245, v245
	v_fma_f32 v4, v4, v237, v156
	v_fma_f32 v5, v5, v237, v157
	v_fma_f32 v6, v6, v237, v158
	v_fma_f32 v7, v7, v237, v159
	v_fma_f32 v0, v0, v237, v164
	v_fma_f32 v1, v1, v237, v165
	v_fma_f32 v2, v2, v237, v166
	v_fma_f32 v3, v3, v237, v167
	v_add_f32_e32 v238, 1.0, v238
	v_add_f32_e32 v239, 1.0, v239
	v_add_f32_e32 v240, 1.0, v240
	v_add_f32_e32 v241, 1.0, v241
	v_add_f32_e32 v242, 1.0, v242
	v_add_f32_e32 v243, 1.0, v243
	v_add_f32_e32 v244, 1.0, v244
	v_add_f32_e32 v245, 1.0, v245
	v_rcp_f32_e32 v238, v238
	v_rcp_f32_e32 v239, v239
	v_rcp_f32_e32 v240, v240
	v_rcp_f32_e32 v241, v241
	v_rcp_f32_e32 v242, v242
	v_rcp_f32_e32 v243, v243
	v_rcp_f32_e32 v244, v244
	v_rcp_f32_e32 v245, v245
	v_mul_f32_e32 v12, v12, v4
	v_mul_f32_e32 v13, v13, v5
	v_mul_f32_e32 v14, v14, v6
	v_mul_f32_e32 v15, v15, v7
	v_mul_f32_e32 v8, v8, v0
	v_mul_f32_e32 v9, v9, v1
	v_mul_f32_e32 v10, v10, v2
	v_mul_f32_e32 v11, v11, v3
	v_mul_f32_e32 v12, v12, v238
	v_mul_f32_e32 v13, v13, v239
	v_mul_f32_e32 v14, v14, v240
	v_mul_f32_e32 v15, v15, v241
	v_mul_f32_e32 v8, v8, v242
	v_mul_f32_e32 v9, v9, v243
	v_mul_f32_e32 v10, v10, v244
	v_mul_f32_e32 v11, v11, v245
	v_cvt_pk_bf16_f32 v0, v12, v13
	v_cvt_pk_bf16_f32 v1, v14, v15
	v_cvt_pk_bf16_f32 v2, v8, v9
	v_cvt_pk_bf16_f32 v3, v10, v11
	s_andn2_b64 vcc, exec, s[0:1]
	s_mov_b64 s[0:1], -1
	global_store_dwordx4 v[246:247], v[0:3], off
	s_cbranch_vccnz .LBB0_1118
	s_andn2_b64 vcc, exec, s[10:11]
	s_cbranch_vccnz .LBB0_1117
	s_barrier
	s_branch .LBB0_1117
